# speedup vs baseline: 1.0447x; 1.0340x over previous
; DI unsigned pack2(float a, float b) { v2f f = {a, b}; return __builtin_bit_cast(unsigned, __builtin_convertvector(f, v2bf)); }
; DI float silu_f(float v) { return v / (1.f + fexp(-v)); }
; DI int ltid() { int x = threadIdx.x; asm volatile("" : "+v"(x)); return x; }
;   DI u32x2 pack(int, int, float a, float b, float c, float d, float&) const { u32x2 v; v.x = pack2(a, b); v.y = pack2(c, d); return v; }
; template <class ARow, class Epi>
; DI void gemm_tile(const ARow& arow, long a_kstride, const u16* __restrict__ Bt, long ldb, int K, int m0, int n0,
;                   const Epi& epi, char* smem) {
;     ...
;   if (epi.packed(nh)) {
; #pragma unroll
;     for (int mi = 0; mi < 4; ++mi) {
;       const int m = m0 + wm * 64 + mi * 16 + fr;
;       float ss = 0.f;
;       u32x2 pk[4];
; #pragma unroll
;       for (int ni = 0; ni < 4; ++ni) pk[ni] = epi.pack(m, nh + ni * 16 + fq * 4, acc[ni][mi][0], acc[ni][mi][1], acc[ni][mi][2], acc[ni][mi][3], ss);
;       epi.finish16(m, nh, ss);
;   DI u32x2 pack(int m, int n, float a, float b, float c, float d, float& ss) const {
;     if (n < q_end) { a *= qscale; b *= qscale; c *= qscale; d *= qscale; }
;     else if (n >= z_start) { a = silu_f(a); b = silu_f(b); c = silu_f(c); d = silu_f(d); }
;     ss += a * a + b * b + c * c + d * d;
;     u32x2 v; v.x = pack2(a, b); v.y = pack2(c, d);
;     return v;
;   }
;   DI void finish16(int m, int nh, float ss) const {
;     if (nh >= kn_lo && nh < kn_hi) {
;       ss += __shfl_xor(ss, 16); ss += __shfl_xor(ss, 32);
; #pragma unroll
;       for (int o = 8; o > 0; o >>= 1) ss = fmaxf(ss, __shfl_xor(ss, o));
;       if ((ltid() & 63) == 0) atomicMax(kmax2 + (m >> 13) * 64 + (nh >> 6), __float_as_uint(ss));
;     }
.Lfe_A_not_z:
	s_cmpk_ge_u32 s99, 0x400
	s_cbranch_scc0 .Lfe_A_not_k
	s_cmpk_lt_u32 s99, 0xa00
	s_cbranch_scc0 .Lfe_A_not_k
	s_load_dwordx2 s[100:101], s[56:57], 0x130
	v_and_b32_e32 v152, 1, v84
	v_mul_u32_u24_e32 v152, 12, v152
	v_lshl_add_u32 v152, v84, 2, v152
	v_add_u32_e32 v152, v152, v66
	v_mul_u32_u24_e32 v153, 0xe00, v74
	v_add_u32_e32 v152, v152, v153
	v_lshlrev_b32_e32 v152, 1, v152
	v_add_u32_e32 v153, 0x1c000, v152
	v_add_u32_e32 v154, 0x38000, v152
	v_add_u32_e32 v155, 0x54000, v152
	s_load_dwordx2 s[98:99], s[56:57], 0x100
	v_lshrrev_b32_e32 v174, 6, v66
	v_lshrrev_b32_e32 v175, 13, v74
	v_lshl_add_u32 v174, v175, 6, v174
	v_lshlrev_b32_e32 v174, 2, v174
	s_nop 3
	v_pk_mul_f32 v[156:157], v[60:61], v[60:61]
	v_pk_mul_f32 v[158:159], v[62:63], v[62:63]
	v_pk_mul_f32 v[160:161], v[56:57], v[56:57]
	v_pk_mul_f32 v[162:163], v[58:59], v[58:59]
	v_pk_mul_f32 v[164:165], v[52:53], v[52:53]
	v_pk_mul_f32 v[166:167], v[54:55], v[54:55]
	v_pk_mul_f32 v[168:169], v[48:49], v[48:49]
	v_pk_mul_f32 v[170:171], v[50:51], v[50:51]
	v_add_f32_e32 v172, v157, v156
	v_add_f32_e32 v172, v158, v172
	v_add_f32_e32 v172, v159, v172
	v_add_f32_e32 v173, v161, v160
	v_add_f32_e32 v173, v162, v173
	v_add_f32_e32 v173, v163, v173
	v_add_f32_e32 v172, v172, v173
	v_add_f32_e32 v173, v165, v164
	v_add_f32_e32 v173, v166, v173
	v_add_f32_e32 v173, v167, v173
	v_add_f32_e32 v172, v172, v173
	v_add_f32_e32 v173, v169, v168
	v_add_f32_e32 v173, v170, v173
	v_add_f32_e32 v173, v171, v173
	v_add_f32_e32 v172, v172, v173
	v_mov_b32_e32 v173, v172
	s_nop 1
	v_permlane16_swap_b32_e32 v173, v172
	v_add_f32_e32 v172, v172, v173
	v_mov_b32_e32 v173, v172
	s_nop 1
	v_permlane32_swap_b32_e32 v173, v172
	v_add_f32_e32 v172, v172, v173
	s_nop 1
	v_max_f32_dpp v172, v172, v172 row_ror:8 row_mask:0xf bank_mask:0xf
	s_nop 1
	v_max_f32_dpp v173, v172, v172 row_shl:4 row_mask:0xf bank_mask:0x5
	v_max_f32_dpp v173, v172, v172 row_shr:4 row_mask:0xf bank_mask:0xa
	s_nop 1
	v_max_f32_dpp v172, v173, v173 quad_perm:[2,3,0,1] row_mask:0xf bank_mask:0xf
	s_nop 1
	v_max_f32_dpp v172, v172, v172 quad_perm:[1,0,3,2] row_mask:0xf bank_mask:0xf
	v_mov_b32_e32 v176, v172
	v_pk_mul_f32 v[156:157], v[44:45], v[44:45]
	v_pk_mul_f32 v[158:159], v[46:47], v[46:47]
	v_pk_mul_f32 v[160:161], v[40:41], v[40:41]
	v_pk_mul_f32 v[162:163], v[42:43], v[42:43]
	v_pk_mul_f32 v[164:165], v[36:37], v[36:37]
	v_pk_mul_f32 v[166:167], v[38:39], v[38:39]
	v_pk_mul_f32 v[168:169], v[32:33], v[32:33]
	v_pk_mul_f32 v[170:171], v[34:35], v[34:35]
	v_add_f32_e32 v172, v157, v156
	v_add_f32_e32 v172, v158, v172
	v_add_f32_e32 v172, v159, v172
	v_add_f32_e32 v173, v161, v160
	v_add_f32_e32 v173, v162, v173
	v_add_f32_e32 v173, v163, v173
	v_add_f32_e32 v172, v172, v173
	v_add_f32_e32 v173, v165, v164
	v_add_f32_e32 v173, v166, v173
	v_add_f32_e32 v173, v167, v173
	v_add_f32_e32 v172, v172, v173
	v_add_f32_e32 v173, v169, v168
	v_add_f32_e32 v173, v170, v173
	v_add_f32_e32 v173, v171, v173
	v_add_f32_e32 v172, v172, v173
	v_mov_b32_e32 v173, v172
	s_nop 1
	v_permlane16_swap_b32_e32 v173, v172
	v_add_f32_e32 v172, v172, v173
	v_mov_b32_e32 v173, v172
	s_nop 1
	v_permlane32_swap_b32_e32 v173, v172
	v_add_f32_e32 v172, v172, v173
	s_nop 1
	v_max_f32_dpp v172, v172, v172 row_ror:8 row_mask:0xf bank_mask:0xf
	s_nop 1
	v_max_f32_dpp v173, v172, v172 row_shl:4 row_mask:0xf bank_mask:0x5
	v_max_f32_dpp v173, v172, v172 row_shr:4 row_mask:0xf bank_mask:0xa
	s_nop 1
	v_max_f32_dpp v172, v173, v173 quad_perm:[2,3,0,1] row_mask:0xf bank_mask:0xf
	s_nop 1
	v_max_f32_dpp v172, v172, v172 quad_perm:[1,0,3,2] row_mask:0xf bank_mask:0xf
	v_max_f32_e32 v176, v176, v172
	v_pk_mul_f32 v[156:157], v[28:29], v[28:29]
	v_pk_mul_f32 v[158:159], v[30:31], v[30:31]
	v_pk_mul_f32 v[160:161], v[24:25], v[24:25]
	v_pk_mul_f32 v[162:163], v[26:27], v[26:27]
	v_pk_mul_f32 v[164:165], v[20:21], v[20:21]
	v_pk_mul_f32 v[166:167], v[22:23], v[22:23]
	v_pk_mul_f32 v[168:169], v[16:17], v[16:17]
	v_pk_mul_f32 v[170:171], v[18:19], v[18:19]
	v_add_f32_e32 v172, v157, v156
	v_add_f32_e32 v172, v158, v172
	v_add_f32_e32 v172, v159, v172
	v_add_f32_e32 v173, v161, v160
	v_add_f32_e32 v173, v162, v173
	v_add_f32_e32 v173, v163, v173
	v_add_f32_e32 v172, v172, v173
	v_add_f32_e32 v173, v165, v164
	v_add_f32_e32 v173, v166, v173
	v_add_f32_e32 v173, v167, v173
	v_add_f32_e32 v172, v172, v173
	v_add_f32_e32 v173, v169, v168
	v_add_f32_e32 v173, v170, v173
	v_add_f32_e32 v173, v171, v173
	v_add_f32_e32 v172, v172, v173
	v_mov_b32_e32 v173, v172
	s_nop 1
	v_permlane16_swap_b32_e32 v173, v172
	v_add_f32_e32 v172, v172, v173
	v_mov_b32_e32 v173, v172
	s_nop 1
	v_permlane32_swap_b32_e32 v173, v172
	v_add_f32_e32 v172, v172, v173
	s_nop 1
	v_max_f32_dpp v172, v172, v172 row_ror:8 row_mask:0xf bank_mask:0xf
	s_nop 1
	v_max_f32_dpp v173, v172, v172 row_shl:4 row_mask:0xf bank_mask:0x5
	v_max_f32_dpp v173, v172, v172 row_shr:4 row_mask:0xf bank_mask:0xa
	s_nop 1
	v_max_f32_dpp v172, v173, v173 quad_perm:[2,3,0,1] row_mask:0xf bank_mask:0xf
	s_nop 1
	v_max_f32_dpp v172, v172, v172 quad_perm:[1,0,3,2] row_mask:0xf bank_mask:0xf
	v_max_f32_e32 v176, v176, v172
	v_pk_mul_f32 v[156:157], v[12:13], v[12:13]
	v_pk_mul_f32 v[158:159], v[14:15], v[14:15]
	v_pk_mul_f32 v[160:161], v[8:9], v[8:9]
	v_pk_mul_f32 v[162:163], v[10:11], v[10:11]
	v_pk_mul_f32 v[164:165], v[4:5], v[4:5]
	v_pk_mul_f32 v[166:167], v[6:7], v[6:7]
	v_pk_mul_f32 v[168:169], v[0:1], v[0:1]
	v_pk_mul_f32 v[170:171], v[2:3], v[2:3]
	v_add_f32_e32 v172, v157, v156
	v_add_f32_e32 v172, v158, v172
	v_add_f32_e32 v172, v159, v172
	v_add_f32_e32 v173, v161, v160
	v_add_f32_e32 v173, v162, v173
	v_add_f32_e32 v173, v163, v173
	v_add_f32_e32 v172, v172, v173
	v_add_f32_e32 v173, v165, v164
	v_add_f32_e32 v173, v166, v173
	v_add_f32_e32 v173, v167, v173
	v_add_f32_e32 v172, v172, v173
	v_add_f32_e32 v173, v169, v168
	v_add_f32_e32 v173, v170, v173
	v_add_f32_e32 v173, v171, v173
	v_add_f32_e32 v172, v172, v173
	v_mov_b32_e32 v173, v172
	s_nop 1
	v_permlane16_swap_b32_e32 v173, v172
	v_add_f32_e32 v172, v172, v173
	v_mov_b32_e32 v173, v172
	s_nop 1
	v_permlane32_swap_b32_e32 v173, v172
	v_add_f32_e32 v172, v172, v173
	s_nop 1
	v_max_f32_dpp v172, v172, v172 row_ror:8 row_mask:0xf bank_mask:0xf
	s_nop 1
	v_max_f32_dpp v173, v172, v172 row_shl:4 row_mask:0xf bank_mask:0x5
	v_max_f32_dpp v173, v172, v172 row_shr:4 row_mask:0xf bank_mask:0xa
	s_nop 1
	v_max_f32_dpp v172, v173, v173 quad_perm:[2,3,0,1] row_mask:0xf bank_mask:0xf
	s_nop 1
	v_max_f32_dpp v172, v172, v172 quad_perm:[1,0,3,2] row_mask:0xf bank_mask:0xf
	v_max_f32_e32 v176, v176, v172
	v_and_b32_e32 v175, 63, v222
	v_cmp_eq_u32_e32 vcc, 0, v175
	s_waitcnt lgkmcnt(0)
; DI int ltid() { int x = threadIdx.x; asm volatile("" : "+v"(x)); return x; }
;   DI u32x2 pack(int, int, float a, float b, float c, float d, float&) const { u32x2 v; v.x = pack2(a, b); v.y = pack2(c, d); return v; }
; template <class ARow, class Epi>
; DI void gemm_tile(const ARow& arow, long a_kstride, const u16* __restrict__ Bt, long ldb, int K, int m0, int n0,
;                   const Epi& epi, char* smem) {
;     ...
;       for (int ni = 0; ni < 4; ++ni) pk[ni] = epi.pack(m, nh + ni * 16 + fq * 4, acc[ni][mi][0], acc[ni][mi][1], acc[ni][mi][2], acc[ni][mi][3], ss);
;       epi.finish16(m, nh, ss);
;       u16* rp = epi.rowp(m) + nh;
; #pragma unroll
;       for (int pp = 0; pp < 2; ++pp) {
;         u32x2 a = pk[2 * pp], b = pk[2 * pp + 1];
;         const u32x2 rx = __builtin_amdgcn_permlane16_swap(a.x, b.x, false, false);
;         const u32x2 ry = __builtin_amdgcn_permlane16_swap(a.y, b.y, false, false);
;         const int nst = (fq & 1) ? ((2 * pp + 1) * 16 + (fq - 1) * 4) : ((2 * pp) * 16 + fq * 4);
;         *(u32x4*)(rp + nst) = (u32x4){rx[0], ry[0], rx[1], ry[1]};
;       }
;   DI void finish16(int m, int nh, float ss) const {
;     if (nh >= kn_lo && nh < kn_hi) {
;       ss += __shfl_xor(ss, 16); ss += __shfl_xor(ss, 32);
; #pragma unroll
;       for (int o = 8; o > 0; o >>= 1) ss = fmaxf(ss, __shfl_xor(ss, o));
;       if ((ltid() & 63) == 0) atomicMax(kmax2 + (m >> 13) * 64 + (nh >> 6), __float_as_uint(ss));
;     }
	s_and_b64 exec, exec, vcc
	global_atomic_umax v174, v176, s[98:99]
	s_mov_b64 exec, -1
	s_nop 3
	v_cvt_pk_bf16_f32 v120, v60, v61
	v_cvt_pk_bf16_f32 v121, v62, v63
	v_cvt_pk_bf16_f32 v122, v56, v57
	v_cvt_pk_bf16_f32 v123, v58, v59
	v_cvt_pk_bf16_f32 v124, v52, v53
	v_cvt_pk_bf16_f32 v125, v54, v55
	v_cvt_pk_bf16_f32 v126, v48, v49
	v_cvt_pk_bf16_f32 v127, v50, v51
	s_nop 1
	v_permlane16_swap_b32_e32 v120, v122
	v_permlane16_swap_b32_e32 v121, v123
	v_permlane16_swap_b32_e32 v124, v126
	v_permlane16_swap_b32_e32 v125, v127
	s_waitcnt lgkmcnt(0)
	global_store_dwordx4 v152, v[120:123], s[100:101]
	global_store_dwordx4 v152, v[124:127], s[100:101] offset:64
	v_cvt_pk_bf16_f32 v128, v44, v45
	v_cvt_pk_bf16_f32 v129, v46, v47
	v_cvt_pk_bf16_f32 v130, v40, v41
	v_cvt_pk_bf16_f32 v131, v42, v43
	v_cvt_pk_bf16_f32 v132, v36, v37
	v_cvt_pk_bf16_f32 v133, v38, v39
	v_cvt_pk_bf16_f32 v134, v32, v33
	v_cvt_pk_bf16_f32 v135, v34, v35
	s_nop 1
	v_permlane16_swap_b32_e32 v128, v130
	v_permlane16_swap_b32_e32 v129, v131
	v_permlane16_swap_b32_e32 v132, v134
	v_permlane16_swap_b32_e32 v133, v135
	global_store_dwordx4 v153, v[128:131], s[100:101]
	global_store_dwordx4 v153, v[132:135], s[100:101] offset:64
	v_cvt_pk_bf16_f32 v136, v28, v29
	v_cvt_pk_bf16_f32 v137, v30, v31
	v_cvt_pk_bf16_f32 v138, v24, v25
	v_cvt_pk_bf16_f32 v139, v26, v27
	v_cvt_pk_bf16_f32 v140, v20, v21
	v_cvt_pk_bf16_f32 v141, v22, v23
	v_cvt_pk_bf16_f32 v142, v16, v17
	v_cvt_pk_bf16_f32 v143, v18, v19
	s_nop 1
	v_permlane16_swap_b32_e32 v136, v138
	v_permlane16_swap_b32_e32 v137, v139
	v_permlane16_swap_b32_e32 v140, v142
	v_permlane16_swap_b32_e32 v141, v143
	global_store_dwordx4 v154, v[136:139], s[100:101]
	global_store_dwordx4 v154, v[140:143], s[100:101] offset:64
	v_cvt_pk_bf16_f32 v144, v12, v13
	v_cvt_pk_bf16_f32 v145, v14, v15
	v_cvt_pk_bf16_f32 v146, v8, v9
	v_cvt_pk_bf16_f32 v147, v10, v11
	v_cvt_pk_bf16_f32 v148, v4, v5
	v_cvt_pk_bf16_f32 v149, v6, v7
	v_cvt_pk_bf16_f32 v150, v0, v1
	v_cvt_pk_bf16_f32 v151, v2, v3
	s_nop 1
	v_permlane16_swap_b32_e32 v144, v146
	v_permlane16_swap_b32_e32 v145, v147
	v_permlane16_swap_b32_e32 v148, v150
	v_permlane16_swap_b32_e32 v149, v151
	global_store_dwordx4 v155, v[144:147], s[100:101]
	global_store_dwordx4 v155, v[148:151], s[100:101] offset:64
	s_branch .Lfe_join_A

; DI unsigned pack2(float a, float b) { v2f f = {a, b}; return __builtin_bit_cast(unsigned, __builtin_convertvector(f, v2bf)); }
; DI float silu_f(float v) { return v / (1.f + fexp(-v)); }
; DI int ltid() { int x = threadIdx.x; asm volatile("" : "+v"(x)); return x; }
;   DI u32x2 pack(int, int, float a, float b, float c, float d, float&) const { u32x2 v; v.x = pack2(a, b); v.y = pack2(c, d); return v; }
; template <class ARow, class Epi>
; DI void gemm_tile(const ARow& arow, long a_kstride, const u16* __restrict__ Bt, long ldb, int K, int m0, int n0,
;                   const Epi& epi, char* smem) {
;     ...
;   if (epi.packed(nh)) {
; #pragma unroll
;     for (int mi = 0; mi < 4; ++mi) {
;       const int m = m0 + wm * 64 + mi * 16 + fr;
;       float ss = 0.f;
;       u32x2 pk[4];
; #pragma unroll
;       for (int ni = 0; ni < 4; ++ni) pk[ni] = epi.pack(m, nh + ni * 16 + fq * 4, acc[ni][mi][0], acc[ni][mi][1], acc[ni][mi][2], acc[ni][mi][3], ss);
;       epi.finish16(m, nh, ss);
;   DI u32x2 pack(int m, int n, float a, float b, float c, float d, float& ss) const {
;     if (n < q_end) { a *= qscale; b *= qscale; c *= qscale; d *= qscale; }
;     else if (n >= z_start) { a = silu_f(a); b = silu_f(b); c = silu_f(c); d = silu_f(d); }
;     ss += a * a + b * b + c * c + d * d;
;     u32x2 v; v.x = pack2(a, b); v.y = pack2(c, d);
;     return v;
;   }
;   DI void finish16(int m, int nh, float ss) const {
;     if (nh >= kn_lo && nh < kn_hi) {
;       ss += __shfl_xor(ss, 16); ss += __shfl_xor(ss, 32);
; #pragma unroll
;       for (int o = 8; o > 0; o >>= 1) ss = fmaxf(ss, __shfl_xor(ss, o));
;       if ((ltid() & 63) == 0) atomicMax(kmax2 + (m >> 13) * 64 + (nh >> 6), __float_as_uint(ss));
;     }
.Lfe_B_not_z:
	s_cmpk_ge_u32 s99, 0x400
	s_cbranch_scc0 .Lfe_B_not_k
	s_cmpk_lt_u32 s99, 0x800
	s_cbranch_scc0 .Lfe_B_not_k
	s_load_dwordx2 s[100:101], s[56:57], 0x130
	v_and_b32_e32 v152, 1, v84
	v_mul_u32_u24_e32 v152, 12, v152
	v_lshl_add_u32 v152, v84, 2, v152
	v_add_u32_e32 v152, v152, v68
	v_lshl_add_u32 v152, v66, 12, v152
	v_lshlrev_b32_e32 v152, 1, v152
	v_add_u32_e32 v153, 0x20000, v152
	v_add_u32_e32 v154, 0x40000, v152
	v_add_u32_e32 v155, 0x60000, v152
	s_load_dwordx2 s[98:99], s[56:57], 0x100
	v_lshrrev_b32_e32 v174, 6, v68
	v_lshrrev_b32_e32 v175, 13, v66
	v_lshl_add_u32 v174, v175, 6, v174
	v_lshlrev_b32_e32 v174, 2, v174
	s_nop 3
	v_pk_mul_f32 v[156:157], v[60:61], v[60:61]
	v_pk_mul_f32 v[158:159], v[62:63], v[62:63]
	v_pk_mul_f32 v[160:161], v[56:57], v[56:57]
	v_pk_mul_f32 v[162:163], v[58:59], v[58:59]
	v_pk_mul_f32 v[164:165], v[52:53], v[52:53]
	v_pk_mul_f32 v[166:167], v[54:55], v[54:55]
	v_pk_mul_f32 v[168:169], v[48:49], v[48:49]
	v_pk_mul_f32 v[170:171], v[50:51], v[50:51]
	v_add_f32_e32 v172, v157, v156
	v_add_f32_e32 v172, v158, v172
	v_add_f32_e32 v172, v159, v172
	v_add_f32_e32 v173, v161, v160
	v_add_f32_e32 v173, v162, v173
	v_add_f32_e32 v173, v163, v173
	v_add_f32_e32 v172, v172, v173
	v_add_f32_e32 v173, v165, v164
	v_add_f32_e32 v173, v166, v173
	v_add_f32_e32 v173, v167, v173
	v_add_f32_e32 v172, v172, v173
	v_add_f32_e32 v173, v169, v168
	v_add_f32_e32 v173, v170, v173
	v_add_f32_e32 v173, v171, v173
	v_add_f32_e32 v172, v172, v173
	v_mov_b32_e32 v173, v172
	s_nop 1
	v_permlane16_swap_b32_e32 v173, v172
	v_add_f32_e32 v172, v172, v173
	v_mov_b32_e32 v173, v172
	s_nop 1
	v_permlane32_swap_b32_e32 v173, v172
	v_add_f32_e32 v172, v172, v173
	s_nop 1
	v_max_f32_dpp v172, v172, v172 row_ror:8 row_mask:0xf bank_mask:0xf
	s_nop 1
	v_max_f32_dpp v173, v172, v172 row_shl:4 row_mask:0xf bank_mask:0x5
	v_max_f32_dpp v173, v172, v172 row_shr:4 row_mask:0xf bank_mask:0xa
	s_nop 1
	v_max_f32_dpp v172, v173, v173 quad_perm:[2,3,0,1] row_mask:0xf bank_mask:0xf
	s_nop 1
	v_max_f32_dpp v172, v172, v172 quad_perm:[1,0,3,2] row_mask:0xf bank_mask:0xf
	v_mov_b32_e32 v176, v172
	v_pk_mul_f32 v[156:157], v[44:45], v[44:45]
	v_pk_mul_f32 v[158:159], v[46:47], v[46:47]
	v_pk_mul_f32 v[160:161], v[40:41], v[40:41]
	v_pk_mul_f32 v[162:163], v[42:43], v[42:43]
	v_pk_mul_f32 v[164:165], v[36:37], v[36:37]
	v_pk_mul_f32 v[166:167], v[38:39], v[38:39]
	v_pk_mul_f32 v[168:169], v[32:33], v[32:33]
	v_pk_mul_f32 v[170:171], v[34:35], v[34:35]
	v_add_f32_e32 v172, v157, v156
	v_add_f32_e32 v172, v158, v172
	v_add_f32_e32 v172, v159, v172
	v_add_f32_e32 v173, v161, v160
	v_add_f32_e32 v173, v162, v173
	v_add_f32_e32 v173, v163, v173
	v_add_f32_e32 v172, v172, v173
	v_add_f32_e32 v173, v165, v164
	v_add_f32_e32 v173, v166, v173
	v_add_f32_e32 v173, v167, v173
	v_add_f32_e32 v172, v172, v173
	v_add_f32_e32 v173, v169, v168
	v_add_f32_e32 v173, v170, v173
	v_add_f32_e32 v173, v171, v173
	v_add_f32_e32 v172, v172, v173
	v_mov_b32_e32 v173, v172
	s_nop 1
	v_permlane16_swap_b32_e32 v173, v172
	v_add_f32_e32 v172, v172, v173
	v_mov_b32_e32 v173, v172
	s_nop 1
	v_permlane32_swap_b32_e32 v173, v172
	v_add_f32_e32 v172, v172, v173
	s_nop 1
	v_max_f32_dpp v172, v172, v172 row_ror:8 row_mask:0xf bank_mask:0xf
	s_nop 1
	v_max_f32_dpp v173, v172, v172 row_shl:4 row_mask:0xf bank_mask:0x5
	v_max_f32_dpp v173, v172, v172 row_shr:4 row_mask:0xf bank_mask:0xa
	s_nop 1
	v_max_f32_dpp v172, v173, v173 quad_perm:[2,3,0,1] row_mask:0xf bank_mask:0xf
	s_nop 1
	v_max_f32_dpp v172, v172, v172 quad_perm:[1,0,3,2] row_mask:0xf bank_mask:0xf
	v_max_f32_e32 v176, v176, v172
	v_pk_mul_f32 v[156:157], v[28:29], v[28:29]
	v_pk_mul_f32 v[158:159], v[30:31], v[30:31]
	v_pk_mul_f32 v[160:161], v[24:25], v[24:25]
	v_pk_mul_f32 v[162:163], v[26:27], v[26:27]
	v_pk_mul_f32 v[164:165], v[20:21], v[20:21]
	v_pk_mul_f32 v[166:167], v[22:23], v[22:23]
	v_pk_mul_f32 v[168:169], v[16:17], v[16:17]
	v_pk_mul_f32 v[170:171], v[18:19], v[18:19]
	v_add_f32_e32 v172, v157, v156
	v_add_f32_e32 v172, v158, v172
	v_add_f32_e32 v172, v159, v172
	v_add_f32_e32 v173, v161, v160
	v_add_f32_e32 v173, v162, v173
	v_add_f32_e32 v173, v163, v173
	v_add_f32_e32 v172, v172, v173
	v_add_f32_e32 v173, v165, v164
	v_add_f32_e32 v173, v166, v173
	v_add_f32_e32 v173, v167, v173
	v_add_f32_e32 v172, v172, v173
	v_add_f32_e32 v173, v169, v168
	v_add_f32_e32 v173, v170, v173
	v_add_f32_e32 v173, v171, v173
	v_add_f32_e32 v172, v172, v173
	v_mov_b32_e32 v173, v172
	s_nop 1
	v_permlane16_swap_b32_e32 v173, v172
	v_add_f32_e32 v172, v172, v173
	v_mov_b32_e32 v173, v172
	s_nop 1
	v_permlane32_swap_b32_e32 v173, v172
	v_add_f32_e32 v172, v172, v173
	s_nop 1
	v_max_f32_dpp v172, v172, v172 row_ror:8 row_mask:0xf bank_mask:0xf
	s_nop 1
	v_max_f32_dpp v173, v172, v172 row_shl:4 row_mask:0xf bank_mask:0x5
	v_max_f32_dpp v173, v172, v172 row_shr:4 row_mask:0xf bank_mask:0xa
	s_nop 1
	v_max_f32_dpp v172, v173, v173 quad_perm:[2,3,0,1] row_mask:0xf bank_mask:0xf
	s_nop 1
	v_max_f32_dpp v172, v172, v172 quad_perm:[1,0,3,2] row_mask:0xf bank_mask:0xf
	v_max_f32_e32 v176, v176, v172
	v_pk_mul_f32 v[156:157], v[12:13], v[12:13]
	v_pk_mul_f32 v[158:159], v[14:15], v[14:15]
	v_pk_mul_f32 v[160:161], v[8:9], v[8:9]
	v_pk_mul_f32 v[162:163], v[10:11], v[10:11]
	v_pk_mul_f32 v[164:165], v[4:5], v[4:5]
	v_pk_mul_f32 v[166:167], v[6:7], v[6:7]
	v_pk_mul_f32 v[168:169], v[0:1], v[0:1]
	v_pk_mul_f32 v[170:171], v[2:3], v[2:3]
	v_add_f32_e32 v172, v157, v156
	v_add_f32_e32 v172, v158, v172
	v_add_f32_e32 v172, v159, v172
	v_add_f32_e32 v173, v161, v160
	v_add_f32_e32 v173, v162, v173
	v_add_f32_e32 v173, v163, v173
	v_add_f32_e32 v172, v172, v173
	v_add_f32_e32 v173, v165, v164
	v_add_f32_e32 v173, v166, v173
	v_add_f32_e32 v173, v167, v173
	v_add_f32_e32 v172, v172, v173
	v_add_f32_e32 v173, v169, v168
	v_add_f32_e32 v173, v170, v173
	v_add_f32_e32 v173, v171, v173
	v_add_f32_e32 v172, v172, v173
	v_mov_b32_e32 v173, v172
	s_nop 1
	v_permlane16_swap_b32_e32 v173, v172
	v_add_f32_e32 v172, v172, v173
	v_mov_b32_e32 v173, v172
	s_nop 1
	v_permlane32_swap_b32_e32 v173, v172
	v_add_f32_e32 v172, v172, v173
	s_nop 1
	v_max_f32_dpp v172, v172, v172 row_ror:8 row_mask:0xf bank_mask:0xf
	s_nop 1
	v_max_f32_dpp v173, v172, v172 row_shl:4 row_mask:0xf bank_mask:0x5
	v_max_f32_dpp v173, v172, v172 row_shr:4 row_mask:0xf bank_mask:0xa
	s_nop 1
	v_max_f32_dpp v172, v173, v173 quad_perm:[2,3,0,1] row_mask:0xf bank_mask:0xf
	s_nop 1
	v_max_f32_dpp v172, v172, v172 quad_perm:[1,0,3,2] row_mask:0xf bank_mask:0xf
	v_max_f32_e32 v176, v176, v172
	v_and_b32_e32 v175, 63, v222
	v_cmp_eq_u32_e32 vcc, 0, v175
	s_waitcnt lgkmcnt(0)
; DI int ltid() { int x = threadIdx.x; asm volatile("" : "+v"(x)); return x; }
;   DI u32x2 pack(int, int, float a, float b, float c, float d, float&) const { u32x2 v; v.x = pack2(a, b); v.y = pack2(c, d); return v; }
; template <class ARow, class Epi>
; DI void gemm_tile(const ARow& arow, long a_kstride, const u16* __restrict__ Bt, long ldb, int K, int m0, int n0,
;                   const Epi& epi, char* smem) {
;     ...
;       for (int ni = 0; ni < 4; ++ni) pk[ni] = epi.pack(m, nh + ni * 16 + fq * 4, acc[ni][mi][0], acc[ni][mi][1], acc[ni][mi][2], acc[ni][mi][3], ss);
;       epi.finish16(m, nh, ss);
;       u16* rp = epi.rowp(m) + nh;
; #pragma unroll
;       for (int pp = 0; pp < 2; ++pp) {
;         u32x2 a = pk[2 * pp], b = pk[2 * pp + 1];
;         const u32x2 rx = __builtin_amdgcn_permlane16_swap(a.x, b.x, false, false);
;         const u32x2 ry = __builtin_amdgcn_permlane16_swap(a.y, b.y, false, false);
;         const int nst = (fq & 1) ? ((2 * pp + 1) * 16 + (fq - 1) * 4) : ((2 * pp) * 16 + fq * 4);
;         *(u32x4*)(rp + nst) = (u32x4){rx[0], ry[0], rx[1], ry[1]};
;       }
;   DI void finish16(int m, int nh, float ss) const {
;     if (nh >= kn_lo && nh < kn_hi) {
;       ss += __shfl_xor(ss, 16); ss += __shfl_xor(ss, 32);
; #pragma unroll
;       for (int o = 8; o > 0; o >>= 1) ss = fmaxf(ss, __shfl_xor(ss, o));
;       if ((ltid() & 63) == 0) atomicMax(kmax2 + (m >> 13) * 64 + (nh >> 6), __float_as_uint(ss));
;     }
	s_and_b64 exec, exec, vcc
	global_atomic_umax v174, v176, s[98:99] offset:512
	s_mov_b64 exec, -1
	s_nop 3
	v_cvt_pk_bf16_f32 v120, v60, v61
	v_cvt_pk_bf16_f32 v121, v62, v63
	v_cvt_pk_bf16_f32 v122, v56, v57
	v_cvt_pk_bf16_f32 v123, v58, v59
	v_cvt_pk_bf16_f32 v124, v52, v53
	v_cvt_pk_bf16_f32 v125, v54, v55
	v_cvt_pk_bf16_f32 v126, v48, v49
	v_cvt_pk_bf16_f32 v127, v50, v51
	s_nop 1
	v_permlane16_swap_b32_e32 v120, v122
	v_permlane16_swap_b32_e32 v121, v123
	v_permlane16_swap_b32_e32 v124, v126
	v_permlane16_swap_b32_e32 v125, v127
	s_waitcnt lgkmcnt(0)
	global_store_dwordx4 v152, v[120:123], s[100:101]
	global_store_dwordx4 v152, v[124:127], s[100:101] offset:64
	v_cvt_pk_bf16_f32 v128, v44, v45
	v_cvt_pk_bf16_f32 v129, v46, v47
	v_cvt_pk_bf16_f32 v130, v40, v41
	v_cvt_pk_bf16_f32 v131, v42, v43
	v_cvt_pk_bf16_f32 v132, v36, v37
	v_cvt_pk_bf16_f32 v133, v38, v39
	v_cvt_pk_bf16_f32 v134, v32, v33
	v_cvt_pk_bf16_f32 v135, v34, v35
	s_nop 1
	v_permlane16_swap_b32_e32 v128, v130
	v_permlane16_swap_b32_e32 v129, v131
	v_permlane16_swap_b32_e32 v132, v134
	v_permlane16_swap_b32_e32 v133, v135
	global_store_dwordx4 v153, v[128:131], s[100:101]
	global_store_dwordx4 v153, v[132:135], s[100:101] offset:64
	v_cvt_pk_bf16_f32 v136, v28, v29
	v_cvt_pk_bf16_f32 v137, v30, v31
	v_cvt_pk_bf16_f32 v138, v24, v25
	v_cvt_pk_bf16_f32 v139, v26, v27
	v_cvt_pk_bf16_f32 v140, v20, v21
	v_cvt_pk_bf16_f32 v141, v22, v23
	v_cvt_pk_bf16_f32 v142, v16, v17
	v_cvt_pk_bf16_f32 v143, v18, v19
	s_nop 1
	v_permlane16_swap_b32_e32 v136, v138
	v_permlane16_swap_b32_e32 v137, v139
	v_permlane16_swap_b32_e32 v140, v142
	v_permlane16_swap_b32_e32 v141, v143
	global_store_dwordx4 v154, v[136:139], s[100:101]
	global_store_dwordx4 v154, v[140:143], s[100:101] offset:64
	v_cvt_pk_bf16_f32 v144, v12, v13
	v_cvt_pk_bf16_f32 v145, v14, v15
	v_cvt_pk_bf16_f32 v146, v8, v9
	v_cvt_pk_bf16_f32 v147, v10, v11
	v_cvt_pk_bf16_f32 v148, v4, v5
	v_cvt_pk_bf16_f32 v149, v6, v7
	v_cvt_pk_bf16_f32 v150, v0, v1
	v_cvt_pk_bf16_f32 v151, v2, v3
	s_nop 1
	v_permlane16_swap_b32_e32 v144, v146
	v_permlane16_swap_b32_e32 v145, v147
	v_permlane16_swap_b32_e32 v148, v150
	v_permlane16_swap_b32_e32 v149, v151
	global_store_dwordx4 v155, v[144:147], s[100:101]
	global_store_dwordx4 v155, v[148:151], s[100:101] offset:64
	s_branch .Lfe_join_B
